# gate-up GEMM: SwiGLU epilogue row-statistics loads hoisted to the tile start (prefetched into free VGPRs), epilogue vmcnt(0) dropped
# speedup vs baseline: 1.0219x; 1.0013x over previous
;     __device__ __forceinline__ void operator()(const f32x4 (&acc)[2][2][4][2], const Unit& u, int wr, int wc, int fr_in, int fq_in) const {
;     ...
;         for (int ai = 0; ai < 2; ++ai)
; #pragma unroll
;             for (int m = 0; m < 4; ++m) ssv[ai][m] = SS[row0 + ai * HALF + m * 16];
; template <class Epi, class Sched, bool ALIGN_EPI = false, bool SP2 = false>
; __device__ __forceinline__ void gemm_phase(PG8_LAS unsigned char* lds, const Gemm g, const Sched& S, const Epi& E) {
;     ...
;     f32x4 acc[2][2][4][2];
; #pragma unroll
;     for (int a = 0; a < 2; ++a)
; #pragma unroll
;         for (int b = 0; b < 2; ++b)
; #pragma unroll
;             for (int m = 0; m < 4; ++m)
; #pragma unroll
;                 for (int n = 0; n < 2; ++n) acc[a][b][m][n] = (f32x4){0.f, 0.f, 0.f, 0.f};
;     bf16x8 At[4][2], B0[2][2], B1[2][2];
;     const char* cA = (const char*)g.A + (size_t)cur.pm * tstep; const char* cB = (const char*)g.Bt + (size_t)cur.pn * tstep;
.LBB0_177:
	s_ashr_i32 s19, s18, 31
	s_lshl_b64 s[8:9], s[18:19], 19
	s_add_u32 s22, s58, s8
	s_addc_u32 s23, s59, s9
	s_and_b64 s[8:9], s[0:1], exec
	s_cselect_b32 s19, s23, s27
	s_cselect_b32 s73, s22, s26
	s_ashr_i32 s15, s14, 31
	s_lshl_b64 s[8:9], s[14:15], 19
	s_add_u32 s8, s30, s8
	s_addc_u32 s9, s39, s9
	s_and_b64 s[36:37], s[0:1], exec
	s_cselect_b32 s15, s9, s25
	s_cselect_b32 s74, s8, s24
	s_add_u32 s75, s24, 0x100
	s_addc_u32 s76, s25, 0
	s_add_u32 s24, s26, 0x40080
	v_mov_b32_e32 v2, 0
	s_addc_u32 s25, s27, 0
	s_mov_b32 s77, -2
	v_mov_b32_e32 v3, v2
	v_mov_b32_e32 v4, v2
	v_mov_b32_e32 v5, v2
	v_mov_b32_e32 v10, v2
	v_mov_b32_e32 v11, v2
	v_mov_b32_e32 v12, v2
	v_mov_b32_e32 v13, v2
	v_mov_b32_e32 v22, v2
	v_mov_b32_e32 v23, v2
	v_mov_b32_e32 v24, v2
	v_mov_b32_e32 v25, v2
	v_mov_b32_e32 v26, v2
	v_mov_b32_e32 v27, v2
	v_mov_b32_e32 v28, v2
	v_mov_b32_e32 v29, v2
	v_mov_b32_e32 v38, v2
	v_mov_b32_e32 v39, v2
	v_mov_b32_e32 v40, v2
	v_mov_b32_e32 v41, v2
	v_mov_b32_e32 v42, v2
	v_mov_b32_e32 v43, v2
	v_mov_b32_e32 v44, v2
	v_mov_b32_e32 v45, v2
	v_mov_b32_e32 v54, v2
	v_mov_b32_e32 v55, v2
	v_mov_b32_e32 v56, v2
	v_mov_b32_e32 v57, v2
	v_mov_b32_e32 v58, v2
	v_mov_b32_e32 v59, v2
	v_mov_b32_e32 v60, v2
	v_mov_b32_e32 v61, v2
	v_mov_b32_e32 v6, v2
	v_mov_b32_e32 v7, v2
	v_mov_b32_e32 v8, v2
	v_mov_b32_e32 v9, v2
	v_mov_b32_e32 v14, v2
	v_mov_b32_e32 v15, v2
	v_mov_b32_e32 v16, v2
	v_mov_b32_e32 v17, v2
	v_mov_b32_e32 v18, v2
	v_mov_b32_e32 v19, v2
	v_mov_b32_e32 v20, v2
	v_mov_b32_e32 v21, v2
	v_mov_b32_e32 v30, v2
	v_mov_b32_e32 v31, v2
	v_mov_b32_e32 v32, v2
	v_mov_b32_e32 v33, v2
	v_mov_b32_e32 v34, v2
	v_mov_b32_e32 v35, v2
	v_mov_b32_e32 v36, v2
	v_mov_b32_e32 v37, v2
	v_mov_b32_e32 v46, v2
	v_mov_b32_e32 v47, v2
	v_mov_b32_e32 v48, v2
	v_mov_b32_e32 v49, v2
	v_mov_b32_e32 v50, v2
	v_mov_b32_e32 v51, v2
	v_mov_b32_e32 v52, v2
	v_mov_b32_e32 v53, v2
	v_mov_b32_e32 v62, v2
	v_mov_b32_e32 v63, v2
	v_mov_b32_e32 v64, v2
	v_mov_b32_e32 v65, v2
	v_mov_b32_e32 v70, v2
	v_mov_b32_e32 v71, v2
	v_mov_b32_e32 v72, v2
	v_mov_b32_e32 v73, v2
	v_mov_b32_e32 v74, v2
	v_mov_b32_e32 v75, v2
	v_mov_b32_e32 v76, v2
	v_mov_b32_e32 v77, v2
	v_mov_b32_e32 v86, v2
	v_mov_b32_e32 v87, v2
	v_mov_b32_e32 v88, v2
	v_mov_b32_e32 v89, v2
	v_mov_b32_e32 v90, v2
	v_mov_b32_e32 v91, v2
	v_mov_b32_e32 v92, v2
	v_mov_b32_e32 v93, v2
	v_mov_b32_e32 v102, v2
	v_mov_b32_e32 v103, v2
	v_mov_b32_e32 v104, v2
	v_mov_b32_e32 v105, v2
	v_mov_b32_e32 v110, v2
	v_mov_b32_e32 v111, v2
	v_mov_b32_e32 v112, v2
	v_mov_b32_e32 v113, v2
	v_mov_b32_e32 v114, v2
	v_mov_b32_e32 v115, v2
	v_mov_b32_e32 v116, v2
	v_mov_b32_e32 v117, v2
	v_mov_b32_e32 v122, v2
	v_mov_b32_e32 v123, v2
	v_mov_b32_e32 v124, v2
	v_mov_b32_e32 v125, v2
	v_mov_b32_e32 v66, v2
	v_mov_b32_e32 v67, v2
	v_mov_b32_e32 v68, v2
	v_mov_b32_e32 v69, v2
	v_mov_b32_e32 v78, v2
	v_mov_b32_e32 v79, v2
	v_mov_b32_e32 v80, v2
	v_mov_b32_e32 v81, v2
	v_mov_b32_e32 v82, v2
	v_mov_b32_e32 v83, v2
	v_mov_b32_e32 v84, v2
	v_mov_b32_e32 v85, v2
	v_mov_b32_e32 v94, v2
	v_mov_b32_e32 v95, v2
	v_mov_b32_e32 v96, v2
	v_mov_b32_e32 v97, v2
	v_mov_b32_e32 v98, v2
	v_mov_b32_e32 v99, v2
	v_mov_b32_e32 v100, v2
	v_mov_b32_e32 v101, v2
	v_mov_b32_e32 v106, v2
	v_mov_b32_e32 v107, v2
	v_mov_b32_e32 v108, v2
	v_mov_b32_e32 v109, v2
	v_mov_b32_e32 v118, v2
	v_mov_b32_e32 v119, v2
	v_mov_b32_e32 v120, v2
	v_mov_b32_e32 v121, v2
	v_mov_b32_e32 v126, v2
	v_mov_b32_e32 v127, v2
	v_mov_b32_e32 v128, v2
	v_mov_b32_e32 v129, v2
	v_mov_b32_e32 v224, s72
	v_lshl_add_u32 v224, v224, 8, s61
	v_and_or_b32 v224, v252, 15, v224
	v_ashrrev_i32_e32 v225, 31, v224
	v_lshl_add_u64 v[226:227], v[224:225], 2, s[12:13]
	global_load_dword v232, v[226:227], off
	global_load_dword v233, v[226:227], off offset:64
	global_load_dword v234, v[226:227], off offset:128
	global_load_dword v235, v[226:227], off offset:192
	global_load_dword v236, v[226:227], off offset:512
	global_load_dword v237, v[226:227], off offset:576
	global_load_dword v238, v[226:227], off offset:640
	global_load_dword v239, v[226:227], off offset:704

; __device__ __forceinline__ unsigned cvt_pk_bf16(float lo, float hi) { unsigned r; asm volatile("v_cvt_pk_bf16_f32 %0, %1, %2" : "=v"(r) : "v"(lo), "v"(hi)); return r; }
;     __device__ __forceinline__ void operator()(const f32x4 (&acc)[2][2][4][2], const Unit& u, int wr, int wc, int fr_in, int fq_in) const {
;     ...
; #pragma unroll
;         for (int ai = 0; ai < 2; ++ai)
; #pragma unroll
;             for (int m = 0; m < 4; ++m) {
;                 const int row = row0 + ai * HALF + m * 16;
;                 const float rs = __builtin_amdgcn_rsqf(ssv[ai][m] * (1.0f / 1024.0f) + 1e-6f);
;                 const float kneg = -1.4426950408889634f * rs, rs2 = rs * rs;
;                 bf16_t* rowp = O + (size_t)row * ldo + col0;
;                 const f32x4 g0 = acc[ai][0][m][0], g1 = acc[ai][0][m][1], u0 = acc[ai][1][m][0], u1 = acc[ai][1][m][1];
;                 const f32x2 a0 = silu_mul2((f32x2){g0[0], g0[1]}, (f32x2){u0[0], u0[1]}, kneg, rs2), a1 = silu_mul2((f32x2){g0[2], g0[3]}, (f32x2){u0[2], u0[3]}, kneg, rs2);
;                 const f32x2 a2 = silu_mul2((f32x2){g1[0], g1[1]}, (f32x2){u1[0], u1[1]}, kneg, rs2), a3 = silu_mul2((f32x2){g1[2], g1[3]}, (f32x2){u1[2], u1[3]}, kneg, rs2);
;                 u32x4 w; w.x = cvt_pk_bf16(a0.x, a0.y); w.y = cvt_pk_bf16(a1.x, a1.y); w.z = cvt_pk_bf16(a2.x, a2.y); w.w = cvt_pk_bf16(a3.x, a3.y);
;                 *(u32x4*)rowp = w;
.LBB0_181:
	s_lshl_b32 s15, s72, 8
	v_mov_b32_e32 v140, v252
	s_add_i32 s15, s15, s61
	v_pk_mul_f32 v[122:123], v[126:127], v[122:123]
	v_and_or_b32 v142, v140, 15, s15
	v_ashrrev_i32_e32 v143, 31, v142
	v_lshrrev_b32_e32 v158, 1, v140
	v_lshl_add_u64 v[140:141], v[142:143], 2, s[12:13]
	s_lshl_b32 s15, s71, 7
	v_and_or_b32 v140, v158, 24, s15
	v_or_b32_e32 v158, s64, v140
	v_ashrrev_i32_e32 v159, 31, v158
	v_or_b32_e32 v161, 16, v142
	v_or_b32_e32 v156, 32, v142
	v_or_b32_e32 v154, 48, v142
	v_add_u32_e32 v152, 0x80, v142
	v_add_u32_e32 v150, 0x90, v142
	v_add_u32_e32 v148, 0xa0, v142
	v_add_u32_e32 v146, 0xb0, v142
	v_pk_mul_f32 v[124:125], v[128:129], v[124:125]
	v_pk_mul_f32 v[114:115], v[118:119], v[114:115]
	v_pk_mul_f32 v[116:117], v[120:121], v[116:117]
	v_pk_mul_f32 v[112:113], v[108:109], v[112:113]
	v_pk_mul_f32 v[104:105], v[100:101], v[104:105]
	v_pk_mul_f32 v[90:91], v[94:95], v[90:91]
	v_pk_mul_f32 v[92:93], v[96:97], v[92:93]
	v_pk_mul_f32 v[88:89], v[84:85], v[88:89]
	v_pk_mul_f32 v[74:75], v[78:79], v[74:75]
	v_pk_mul_f32 v[76:77], v[80:81], v[76:77]
	v_pk_mul_f32 v[72:73], v[68:69], v[72:73]
	v_pk_mul_f32 v[58:59], v[62:63], v[58:59]
	v_pk_mul_f32 v[60:61], v[64:65], v[60:61]
	v_pk_mul_f32 v[56:57], v[52:53], v[56:57]
	v_pk_mul_f32 v[42:43], v[46:47], v[42:43]
	v_pk_mul_f32 v[44:45], v[48:49], v[44:45]
	v_pk_mul_f32 v[40:41], v[36:37], v[40:41]
	v_pk_mul_f32 v[26:27], v[30:31], v[26:27]
	v_pk_mul_f32 v[28:29], v[32:33], v[28:29]
	v_pk_mul_f32 v[24:25], v[20:21], v[24:25]
	v_pk_mul_f32 v[10:11], v[14:15], v[10:11]
	v_pk_mul_f32 v[12:13], v[16:17], v[12:13]
	v_pk_mul_f32 v[2:3], v[6:7], v[2:3]
	v_pk_mul_f32 v[4:5], v[8:9], v[4:5]
	s_andn2_b64 vcc, exec, s[0:1]
	s_waitcnt lgkmcnt(0)
	v_fmamk_f32 v140, v232, 0x3a800000, v218
	v_rsq_f32_e32 v140, v140
	s_nop 0
	v_mul_f32_e32 v160, 0xbfb8aa3b, v140
	v_mul_f32_e32 v162, v140, v140
	v_mov_b64_e32 v[140:141], s[16:17]
	v_mad_i64_i32 v[164:165], s[24:25], v142, s55, v[140:141]
	v_lshlrev_b64 v[142:143], 1, v[158:159]
	v_lshl_add_u64 v[158:159], v[164:165], 0, v[142:143]
	v_pk_mul_f32 v[164:165], v[126:127], v[160:161] op_sel_hi:[1,0]
	s_nop 0
	v_exp_f32_e32 v164, v164
	v_exp_f32_e32 v165, v165
	s_nop 0
	v_pk_add_f32 v[164:165], v[164:165], 1.0 op_sel_hi:[1,0]
	s_nop 0
	v_rcp_f32_e32 v164, v164
	v_rcp_f32_e32 v165, v165
	s_nop 0
	v_pk_mul_f32 v[126:127], v[162:163], v[164:165] op_sel_hi:[0,1]
	v_pk_mul_f32 v[122:123], v[122:123], v[126:127]
	v_pk_mul_f32 v[126:127], v[128:129], v[160:161] op_sel_hi:[1,0]
	s_nop 0
	v_exp_f32_e32 v126, v126
	v_exp_f32_e32 v127, v127
	s_nop 0
	v_pk_add_f32 v[126:127], v[126:127], 1.0 op_sel_hi:[1,0]
	s_nop 0
	v_rcp_f32_e32 v126, v126
	v_rcp_f32_e32 v127, v127
	s_nop 0
	v_pk_mul_f32 v[126:127], v[162:163], v[126:127] op_sel_hi:[0,1]
	v_pk_mul_f32 v[124:125], v[124:125], v[126:127]
	v_pk_mul_f32 v[126:127], v[118:119], v[160:161] op_sel_hi:[1,0]
	s_nop 0
	v_exp_f32_e32 v126, v126
	v_exp_f32_e32 v127, v127
	s_nop 0
	v_pk_add_f32 v[126:127], v[126:127], 1.0 op_sel_hi:[1,0]
	s_nop 0
	v_rcp_f32_e32 v126, v126
	v_rcp_f32_e32 v127, v127
	s_nop 0
	v_pk_mul_f32 v[118:119], v[162:163], v[126:127] op_sel_hi:[0,1]
	v_pk_mul_f32 v[118:119], v[114:115], v[118:119]
	v_pk_mul_f32 v[114:115], v[120:121], v[160:161] op_sel_hi:[1,0]
	s_nop 0
	v_exp_f32_e32 v114, v114
	v_exp_f32_e32 v115, v115
	s_nop 0
	v_pk_add_f32 v[114:115], v[114:115], 1.0 op_sel_hi:[1,0]
	s_nop 0
	v_rcp_f32_e32 v114, v114
	v_rcp_f32_e32 v115, v115
	s_nop 0
	v_pk_mul_f32 v[114:115], v[162:163], v[114:115] op_sel_hi:[0,1]
	v_pk_mul_f32 v[120:121], v[116:117], v[114:115]
	v_cvt_pk_bf16_f32 v114, v122, v123
	v_cvt_pk_bf16_f32 v115, v124, v125
	v_cvt_pk_bf16_f32 v116, v118, v119
	s_nop 0
	v_cvt_pk_bf16_f32 v117, v120, v121
	flat_store_dwordx4 v[158:159], v[114:117]
	s_nop 1
	v_fmamk_f32 v114, v233, 0x3a800000, v218
	v_rsq_f32_e32 v114, v114
	s_nop 0
	v_mul_f32_e32 v118, 0xbfb8aa3b, v114
	v_pk_mul_f32 v[120:121], v[106:107], v[118:119] op_sel_hi:[1,0]
	v_mul_f32_e32 v116, v114, v114
	v_exp_f32_e32 v120, v120
	v_exp_f32_e32 v121, v121
	v_pk_mul_f32 v[106:107], v[106:107], v[110:111]
	v_pk_mul_f32 v[108:109], v[108:109], v[118:119] op_sel_hi:[1,0]
	v_mad_i64_i32 v[114:115], s[24:25], v161, s55, v[140:141]
	v_pk_add_f32 v[120:121], v[120:121], 1.0 op_sel_hi:[1,0]
	v_exp_f32_e32 v108, v108
	v_rcp_f32_e32 v120, v120
	v_rcp_f32_e32 v121, v121
	v_exp_f32_e32 v109, v109
	v_lshl_add_u64 v[114:115], v[114:115], 0, v[142:143]
	v_pk_mul_f32 v[110:111], v[116:117], v[120:121] op_sel_hi:[0,1]
	v_pk_mul_f32 v[106:107], v[106:107], v[110:111]
	v_pk_mul_f32 v[110:111], v[98:99], v[118:119] op_sel_hi:[1,0]
	v_pk_mul_f32 v[98:99], v[98:99], v[102:103]
	v_exp_f32_e32 v110, v110
	v_exp_f32_e32 v111, v111
	v_pk_add_f32 v[108:109], v[108:109], 1.0 op_sel_hi:[1,0]
	v_pk_add_f32 v[110:111], v[110:111], 1.0 op_sel_hi:[1,0]
	s_nop 0
	v_rcp_f32_e32 v110, v110
	v_rcp_f32_e32 v111, v111
	v_rcp_f32_e32 v108, v108
	v_rcp_f32_e32 v109, v109
	v_pk_mul_f32 v[102:103], v[116:117], v[110:111] op_sel_hi:[0,1]
	v_pk_mul_f32 v[102:103], v[98:99], v[102:103]
	v_pk_mul_f32 v[98:99], v[100:101], v[118:119] op_sel_hi:[1,0]
	v_pk_mul_f32 v[108:109], v[116:117], v[108:109] op_sel_hi:[0,1]
	v_exp_f32_e32 v98, v98
	v_exp_f32_e32 v99, v99
	v_pk_mul_f32 v[108:109], v[112:113], v[108:109]
	v_pk_add_f32 v[98:99], v[98:99], 1.0 op_sel_hi:[1,0]
	s_nop 0
	v_rcp_f32_e32 v98, v98
	v_rcp_f32_e32 v99, v99
	s_nop 0
	v_pk_mul_f32 v[98:99], v[116:117], v[98:99] op_sel_hi:[0,1]
	v_pk_mul_f32 v[104:105], v[104:105], v[98:99]
	v_cvt_pk_bf16_f32 v98, v106, v107
	v_cvt_pk_bf16_f32 v99, v108, v109
	v_cvt_pk_bf16_f32 v100, v102, v103
	v_mad_i64_i32 v[102:103], s[24:25], v156, s55, v[140:141]
; __device__ __forceinline__ unsigned cvt_pk_bf16(float lo, float hi) { unsigned r; asm volatile("v_cvt_pk_bf16_f32 %0, %1, %2" : "=v"(r) : "v"(lo), "v"(hi)); return r; }
;     __device__ __forceinline__ void operator()(const f32x4 (&acc)[2][2][4][2], const Unit& u, int wr, int wc, int fr_in, int fq_in) const {
;     ...
; #pragma unroll
;         for (int ai = 0; ai < 2; ++ai)
; #pragma unroll
;             for (int m = 0; m < 4; ++m) {
;                 const int row = row0 + ai * HALF + m * 16;
;                 const float rs = __builtin_amdgcn_rsqf(ssv[ai][m] * (1.0f / 1024.0f) + 1e-6f);
;                 const float kneg = -1.4426950408889634f * rs, rs2 = rs * rs;
;                 bf16_t* rowp = O + (size_t)row * ldo + col0;
;                 const f32x4 g0 = acc[ai][0][m][0], g1 = acc[ai][0][m][1], u0 = acc[ai][1][m][0], u1 = acc[ai][1][m][1];
;                 const f32x2 a0 = silu_mul2((f32x2){g0[0], g0[1]}, (f32x2){u0[0], u0[1]}, kneg, rs2), a1 = silu_mul2((f32x2){g0[2], g0[3]}, (f32x2){u0[2], u0[3]}, kneg, rs2);
;                 const f32x2 a2 = silu_mul2((f32x2){g1[0], g1[1]}, (f32x2){u1[0], u1[1]}, kneg, rs2), a3 = silu_mul2((f32x2){g1[2], g1[3]}, (f32x2){u1[2], u1[3]}, kneg, rs2);
;                 u32x4 w; w.x = cvt_pk_bf16(a0.x, a0.y); w.y = cvt_pk_bf16(a1.x, a1.y); w.z = cvt_pk_bf16(a2.x, a2.y); w.w = cvt_pk_bf16(a3.x, a3.y);
;                 *(u32x4*)rowp = w;
	v_cvt_pk_bf16_f32 v101, v104, v105
	flat_store_dwordx4 v[114:115], v[98:101]
	v_lshl_add_u64 v[102:103], v[102:103], 0, v[142:143]
	s_nop 0
	v_fmamk_f32 v98, v234, 0x3a800000, v218
	v_rsq_f32_e32 v99, v98
	s_nop 0
	v_mul_f32_e32 v98, 0xbfb8aa3b, v99
	v_pk_mul_f32 v[104:105], v[94:95], v[98:99] op_sel_hi:[1,0]
	v_mul_f32_e32 v100, v99, v99
	v_exp_f32_e32 v104, v104
	v_exp_f32_e32 v105, v105
	s_nop 0
	v_pk_add_f32 v[104:105], v[104:105], 1.0 op_sel_hi:[1,0]
	s_nop 0
	v_rcp_f32_e32 v104, v104
	v_rcp_f32_e32 v105, v105
	s_nop 0
	v_pk_mul_f32 v[94:95], v[100:101], v[104:105] op_sel_hi:[0,1]
	v_pk_mul_f32 v[90:91], v[90:91], v[94:95]
	v_pk_mul_f32 v[94:95], v[96:97], v[98:99] op_sel_hi:[1,0]
	s_nop 0
	v_exp_f32_e32 v94, v94
	v_exp_f32_e32 v95, v95
	s_nop 0
	v_pk_add_f32 v[94:95], v[94:95], 1.0 op_sel_hi:[1,0]
	s_nop 0
	v_rcp_f32_e32 v94, v94
	v_rcp_f32_e32 v95, v95
	s_nop 0
	v_pk_mul_f32 v[94:95], v[100:101], v[94:95] op_sel_hi:[0,1]
	v_pk_mul_f32 v[92:93], v[92:93], v[94:95]
	v_pk_mul_f32 v[94:95], v[82:83], v[98:99] op_sel_hi:[1,0]
	v_pk_mul_f32 v[82:83], v[82:83], v[86:87]
	v_exp_f32_e32 v94, v94
	v_exp_f32_e32 v95, v95
	s_nop 0
	v_pk_add_f32 v[94:95], v[94:95], 1.0 op_sel_hi:[1,0]
	s_nop 0
	v_rcp_f32_e32 v94, v94
	v_rcp_f32_e32 v95, v95
	s_nop 0
	v_pk_mul_f32 v[86:87], v[100:101], v[94:95] op_sel_hi:[0,1]
	v_pk_mul_f32 v[86:87], v[82:83], v[86:87]
	v_pk_mul_f32 v[82:83], v[84:85], v[98:99] op_sel_hi:[1,0]
	s_nop 0
	v_exp_f32_e32 v82, v82
	v_exp_f32_e32 v83, v83
	s_nop 0
	v_pk_add_f32 v[82:83], v[82:83], 1.0 op_sel_hi:[1,0]
	s_nop 0
	v_rcp_f32_e32 v82, v82
	v_rcp_f32_e32 v83, v83
	s_nop 0
	v_pk_mul_f32 v[82:83], v[100:101], v[82:83] op_sel_hi:[0,1]
	v_pk_mul_f32 v[88:89], v[88:89], v[82:83]
	v_cvt_pk_bf16_f32 v82, v90, v91
	v_cvt_pk_bf16_f32 v83, v92, v93
	v_cvt_pk_bf16_f32 v84, v86, v87
	v_mad_i64_i32 v[86:87], s[24:25], v154, s55, v[140:141]
	v_cvt_pk_bf16_f32 v85, v88, v89
	flat_store_dwordx4 v[102:103], v[82:85]
	v_lshl_add_u64 v[86:87], v[86:87], 0, v[142:143]
	s_nop 0
	v_fmamk_f32 v82, v235, 0x3a800000, v218
	v_rsq_f32_e32 v83, v82
	s_nop 0
	v_mul_f32_e32 v82, 0xbfb8aa3b, v83
	v_pk_mul_f32 v[88:89], v[78:79], v[82:83] op_sel_hi:[1,0]
	v_mul_f32_e32 v84, v83, v83
	v_exp_f32_e32 v88, v88
	v_exp_f32_e32 v89, v89
	s_nop 0
	v_pk_add_f32 v[88:89], v[88:89], 1.0 op_sel_hi:[1,0]
	s_nop 0
	v_rcp_f32_e32 v88, v88
	v_rcp_f32_e32 v89, v89
	s_nop 0
	v_pk_mul_f32 v[78:79], v[84:85], v[88:89] op_sel_hi:[0,1]
	v_pk_mul_f32 v[74:75], v[74:75], v[78:79]
	v_pk_mul_f32 v[78:79], v[80:81], v[82:83] op_sel_hi:[1,0]
	s_nop 0
	v_exp_f32_e32 v78, v78
	v_exp_f32_e32 v79, v79
	s_nop 0
	v_pk_add_f32 v[78:79], v[78:79], 1.0 op_sel_hi:[1,0]
	s_nop 0
	v_rcp_f32_e32 v78, v78
	v_rcp_f32_e32 v79, v79
	s_nop 0
	v_pk_mul_f32 v[78:79], v[84:85], v[78:79] op_sel_hi:[0,1]
	v_pk_mul_f32 v[76:77], v[76:77], v[78:79]
	v_pk_mul_f32 v[78:79], v[66:67], v[82:83] op_sel_hi:[1,0]
	v_pk_mul_f32 v[66:67], v[66:67], v[70:71]
	v_exp_f32_e32 v78, v78
	v_exp_f32_e32 v79, v79
	s_nop 0
	v_pk_add_f32 v[78:79], v[78:79], 1.0 op_sel_hi:[1,0]
	s_nop 0
	v_rcp_f32_e32 v78, v78
	v_rcp_f32_e32 v79, v79
	s_nop 0
	v_pk_mul_f32 v[70:71], v[84:85], v[78:79] op_sel_hi:[0,1]
	v_pk_mul_f32 v[70:71], v[66:67], v[70:71]
	v_pk_mul_f32 v[66:67], v[68:69], v[82:83] op_sel_hi:[1,0]
	s_nop 0
	v_exp_f32_e32 v66, v66
	v_exp_f32_e32 v67, v67
	s_nop 0
	v_pk_add_f32 v[66:67], v[66:67], 1.0 op_sel_hi:[1,0]
	s_nop 0
	v_rcp_f32_e32 v66, v66
	v_rcp_f32_e32 v67, v67
	s_nop 0
	v_pk_mul_f32 v[66:67], v[84:85], v[66:67] op_sel_hi:[0,1]
	v_pk_mul_f32 v[72:73], v[72:73], v[66:67]
	v_cvt_pk_bf16_f32 v66, v74, v75
	v_cvt_pk_bf16_f32 v67, v76, v77
	v_cvt_pk_bf16_f32 v68, v70, v71
	v_mad_i64_i32 v[70:71], s[24:25], v152, s55, v[140:141]
	v_cvt_pk_bf16_f32 v69, v72, v73
	flat_store_dwordx4 v[86:87], v[66:69]
	v_lshl_add_u64 v[70:71], v[70:71], 0, v[142:143]
	s_nop 0
	v_fmamk_f32 v66, v236, 0x3a800000, v218
	v_rsq_f32_e32 v67, v66
	s_nop 0
	v_mul_f32_e32 v66, 0xbfb8aa3b, v67
	v_pk_mul_f32 v[72:73], v[62:63], v[66:67] op_sel_hi:[1,0]
	v_mul_f32_e32 v68, v67, v67
	v_exp_f32_e32 v72, v72
	v_exp_f32_e32 v73, v73
	s_nop 0
	v_pk_add_f32 v[72:73], v[72:73], 1.0 op_sel_hi:[1,0]
	s_nop 0
	v_rcp_f32_e32 v72, v72
	v_rcp_f32_e32 v73, v73
	s_nop 0
	v_pk_mul_f32 v[62:63], v[68:69], v[72:73] op_sel_hi:[0,1]
	v_pk_mul_f32 v[58:59], v[58:59], v[62:63]
	v_pk_mul_f32 v[62:63], v[64:65], v[66:67] op_sel_hi:[1,0]
	s_nop 0
	v_exp_f32_e32 v62, v62
	v_exp_f32_e32 v63, v63
	s_nop 0
	v_pk_add_f32 v[62:63], v[62:63], 1.0 op_sel_hi:[1,0]
	s_nop 0
	v_rcp_f32_e32 v62, v62
	v_rcp_f32_e32 v63, v63
	s_nop 0
	v_pk_mul_f32 v[62:63], v[68:69], v[62:63] op_sel_hi:[0,1]
	v_pk_mul_f32 v[60:61], v[60:61], v[62:63]
	v_pk_mul_f32 v[62:63], v[50:51], v[66:67] op_sel_hi:[1,0]
	v_pk_mul_f32 v[50:51], v[50:51], v[54:55]
	v_exp_f32_e32 v62, v62
	v_exp_f32_e32 v63, v63
	s_nop 0
	v_pk_add_f32 v[62:63], v[62:63], 1.0 op_sel_hi:[1,0]
	s_nop 0
	v_rcp_f32_e32 v62, v62
	v_rcp_f32_e32 v63, v63
	s_nop 0
	v_pk_mul_f32 v[54:55], v[68:69], v[62:63] op_sel_hi:[0,1]
	v_pk_mul_f32 v[54:55], v[50:51], v[54:55]
	v_pk_mul_f32 v[50:51], v[52:53], v[66:67] op_sel_hi:[1,0]
	s_nop 0
	v_exp_f32_e32 v50, v50
	v_exp_f32_e32 v51, v51
	s_nop 0
	v_pk_add_f32 v[50:51], v[50:51], 1.0 op_sel_hi:[1,0]
	s_nop 0
	v_rcp_f32_e32 v50, v50
	v_rcp_f32_e32 v51, v51
	s_nop 0
	v_pk_mul_f32 v[50:51], v[68:69], v[50:51] op_sel_hi:[0,1]
	v_pk_mul_f32 v[56:57], v[56:57], v[50:51]
	v_cvt_pk_bf16_f32 v50, v58, v59
	v_cvt_pk_bf16_f32 v51, v60, v61
	v_cvt_pk_bf16_f32 v52, v54, v55
	v_mad_i64_i32 v[54:55], s[24:25], v150, s55, v[140:141]
	v_cvt_pk_bf16_f32 v53, v56, v57
; __device__ __forceinline__ unsigned cvt_pk_bf16(float lo, float hi) { unsigned r; asm volatile("v_cvt_pk_bf16_f32 %0, %1, %2" : "=v"(r) : "v"(lo), "v"(hi)); return r; }
; #define PG8_BAR __builtin_amdgcn_s_barrier()
;     __device__ __forceinline__ void operator()(const f32x4 (&acc)[2][2][4][2], const Unit& u, int wr, int wc, int fr_in, int fq_in) const {
;     ...
; #pragma unroll
;         for (int ai = 0; ai < 2; ++ai)
; #pragma unroll
;             for (int m = 0; m < 4; ++m) {
;                 const int row = row0 + ai * HALF + m * 16;
;                 const float rs = __builtin_amdgcn_rsqf(ssv[ai][m] * (1.0f / 1024.0f) + 1e-6f);
;                 const float kneg = -1.4426950408889634f * rs, rs2 = rs * rs;
;                 bf16_t* rowp = O + (size_t)row * ldo + col0;
;                 const f32x4 g0 = acc[ai][0][m][0], g1 = acc[ai][0][m][1], u0 = acc[ai][1][m][0], u1 = acc[ai][1][m][1];
;                 const f32x2 a0 = silu_mul2((f32x2){g0[0], g0[1]}, (f32x2){u0[0], u0[1]}, kneg, rs2), a1 = silu_mul2((f32x2){g0[2], g0[3]}, (f32x2){u0[2], u0[3]}, kneg, rs2);
;                 const f32x2 a2 = silu_mul2((f32x2){g1[0], g1[1]}, (f32x2){u1[0], u1[1]}, kneg, rs2), a3 = silu_mul2((f32x2){g1[2], g1[3]}, (f32x2){u1[2], u1[3]}, kneg, rs2);
;                 u32x4 w; w.x = cvt_pk_bf16(a0.x, a0.y); w.y = cvt_pk_bf16(a1.x, a1.y); w.z = cvt_pk_bf16(a2.x, a2.y); w.w = cvt_pk_bf16(a3.x, a3.y);
;                 *(u32x4*)rowp = w;
; template <class Epi, class Sched, bool ALIGN_EPI = false, bool SP2 = false>
; __device__ __forceinline__ void gemm_phase(PG8_LAS unsigned char* lds, const Gemm g, const Sched& S, const Epi& E) {
;     ...
;         if constexpr (ALIGN_EPI) { if (wr == 0) PG8_BAR; }
;         if constexpr (!Epi::AFTER_DRAIN) { E(acc, cur, wr, wc, fr, fq); S.done(cur); }
;         if (!has_next) break;
; #pragma unroll
;         for (int a = 0; a < 2; ++a)
; #pragma unroll
;             for (int b = 0; b < 2; ++b)
; #pragma unroll
;                 for (int m = 0; m < 4; ++m)
; #pragma unroll
;                     for (int n = 0; n < 2; ++n) acc[a][b][m][n] = (f32x4){0.f, 0.f, 0.f, 0.f};
;         cur = nxt; cA = nA; cB = nB; ++ui;
;         if constexpr (ALIGN_EPI) { if (wr == 1) PG8_BAR; }
	flat_store_dwordx4 v[70:71], v[50:53]
	v_lshl_add_u64 v[54:55], v[54:55], 0, v[142:143]
	s_nop 0
	v_fmamk_f32 v50, v237, 0x3a800000, v218
	v_rsq_f32_e32 v51, v50
	s_nop 0
	v_mul_f32_e32 v50, 0xbfb8aa3b, v51
	v_pk_mul_f32 v[56:57], v[46:47], v[50:51] op_sel_hi:[1,0]
	v_mul_f32_e32 v52, v51, v51
	v_exp_f32_e32 v56, v56
	v_exp_f32_e32 v57, v57
	s_nop 0
	v_pk_add_f32 v[56:57], v[56:57], 1.0 op_sel_hi:[1,0]
	s_nop 0
	v_rcp_f32_e32 v56, v56
	v_rcp_f32_e32 v57, v57
	s_nop 0
	v_pk_mul_f32 v[46:47], v[52:53], v[56:57] op_sel_hi:[0,1]
	v_pk_mul_f32 v[42:43], v[42:43], v[46:47]
	v_pk_mul_f32 v[46:47], v[48:49], v[50:51] op_sel_hi:[1,0]
	s_nop 0
	v_exp_f32_e32 v46, v46
	v_exp_f32_e32 v47, v47
	s_nop 0
	v_pk_add_f32 v[46:47], v[46:47], 1.0 op_sel_hi:[1,0]
	s_nop 0
	v_rcp_f32_e32 v46, v46
	v_rcp_f32_e32 v47, v47
	s_nop 0
	v_pk_mul_f32 v[46:47], v[52:53], v[46:47] op_sel_hi:[0,1]
	v_pk_mul_f32 v[44:45], v[44:45], v[46:47]
	v_pk_mul_f32 v[46:47], v[34:35], v[50:51] op_sel_hi:[1,0]
	v_pk_mul_f32 v[34:35], v[34:35], v[38:39]
	v_exp_f32_e32 v46, v46
	v_exp_f32_e32 v47, v47
	s_nop 0
	v_pk_add_f32 v[46:47], v[46:47], 1.0 op_sel_hi:[1,0]
	s_nop 0
	v_rcp_f32_e32 v46, v46
	v_rcp_f32_e32 v47, v47
	s_nop 0
	v_pk_mul_f32 v[38:39], v[52:53], v[46:47] op_sel_hi:[0,1]
	v_pk_mul_f32 v[38:39], v[34:35], v[38:39]
	v_pk_mul_f32 v[34:35], v[36:37], v[50:51] op_sel_hi:[1,0]
	s_nop 0
	v_exp_f32_e32 v34, v34
	v_exp_f32_e32 v35, v35
	s_nop 0
	v_pk_add_f32 v[34:35], v[34:35], 1.0 op_sel_hi:[1,0]
	s_nop 0
	v_rcp_f32_e32 v34, v34
	v_rcp_f32_e32 v35, v35
	s_nop 0
	v_pk_mul_f32 v[34:35], v[52:53], v[34:35] op_sel_hi:[0,1]
	v_pk_mul_f32 v[40:41], v[40:41], v[34:35]
	v_cvt_pk_bf16_f32 v34, v42, v43
	v_cvt_pk_bf16_f32 v35, v44, v45
	v_cvt_pk_bf16_f32 v36, v38, v39
	v_mad_i64_i32 v[38:39], s[24:25], v148, s55, v[140:141]
	v_cvt_pk_bf16_f32 v37, v40, v41
	flat_store_dwordx4 v[54:55], v[34:37]
	v_lshl_add_u64 v[38:39], v[38:39], 0, v[142:143]
	s_nop 0
	v_fmamk_f32 v34, v238, 0x3a800000, v218
	v_rsq_f32_e32 v35, v34
	s_nop 0
	v_mul_f32_e32 v34, 0xbfb8aa3b, v35
	v_pk_mul_f32 v[40:41], v[30:31], v[34:35] op_sel_hi:[1,0]
	v_mul_f32_e32 v36, v35, v35
	v_exp_f32_e32 v40, v40
	v_exp_f32_e32 v41, v41
	s_nop 0
	v_pk_add_f32 v[40:41], v[40:41], 1.0 op_sel_hi:[1,0]
	s_nop 0
	v_rcp_f32_e32 v40, v40
	v_rcp_f32_e32 v41, v41
	s_nop 0
	v_pk_mul_f32 v[30:31], v[36:37], v[40:41] op_sel_hi:[0,1]
	v_pk_mul_f32 v[26:27], v[26:27], v[30:31]
	v_pk_mul_f32 v[30:31], v[32:33], v[34:35] op_sel_hi:[1,0]
	s_nop 0
	v_exp_f32_e32 v30, v30
	v_exp_f32_e32 v31, v31
	s_nop 0
	v_pk_add_f32 v[30:31], v[30:31], 1.0 op_sel_hi:[1,0]
	s_nop 0
	v_rcp_f32_e32 v30, v30
	v_rcp_f32_e32 v31, v31
	s_nop 0
	v_pk_mul_f32 v[30:31], v[36:37], v[30:31] op_sel_hi:[0,1]
	v_pk_mul_f32 v[28:29], v[28:29], v[30:31]
	v_pk_mul_f32 v[30:31], v[18:19], v[34:35] op_sel_hi:[1,0]
	v_pk_mul_f32 v[18:19], v[18:19], v[22:23]
	v_exp_f32_e32 v30, v30
	v_exp_f32_e32 v31, v31
	s_nop 0
	v_pk_add_f32 v[30:31], v[30:31], 1.0 op_sel_hi:[1,0]
	s_nop 0
	v_rcp_f32_e32 v30, v30
	v_rcp_f32_e32 v31, v31
	s_nop 0
	v_pk_mul_f32 v[22:23], v[36:37], v[30:31] op_sel_hi:[0,1]
	v_pk_mul_f32 v[22:23], v[18:19], v[22:23]
	v_pk_mul_f32 v[18:19], v[20:21], v[34:35] op_sel_hi:[1,0]
	s_nop 0
	v_exp_f32_e32 v18, v18
	v_exp_f32_e32 v19, v19
	s_nop 0
	v_pk_add_f32 v[18:19], v[18:19], 1.0 op_sel_hi:[1,0]
	s_nop 0
	v_rcp_f32_e32 v18, v18
	v_rcp_f32_e32 v19, v19
	s_nop 0
	v_pk_mul_f32 v[18:19], v[36:37], v[18:19] op_sel_hi:[0,1]
	v_pk_mul_f32 v[24:25], v[24:25], v[18:19]
	v_cvt_pk_bf16_f32 v18, v26, v27
	v_cvt_pk_bf16_f32 v19, v28, v29
	v_cvt_pk_bf16_f32 v20, v22, v23
	v_mad_i64_i32 v[22:23], s[24:25], v146, s55, v[140:141]
	v_cvt_pk_bf16_f32 v21, v24, v25
	flat_store_dwordx4 v[38:39], v[18:21]
	v_lshl_add_u64 v[22:23], v[22:23], 0, v[142:143]
	s_mov_b64 s[24:25], -1
	v_fmamk_f32 v18, v239, 0x3a800000, v218
	v_rsq_f32_e32 v19, v18
	s_nop 0
	v_mul_f32_e32 v18, 0xbfb8aa3b, v19
	v_pk_mul_f32 v[24:25], v[14:15], v[18:19] op_sel_hi:[1,0]
	v_mul_f32_e32 v20, v19, v19
	v_exp_f32_e32 v24, v24
	v_exp_f32_e32 v25, v25
	s_nop 0
	v_pk_add_f32 v[24:25], v[24:25], 1.0 op_sel_hi:[1,0]
	s_nop 0
	v_rcp_f32_e32 v24, v24
	v_rcp_f32_e32 v25, v25
	s_nop 0
	v_pk_mul_f32 v[14:15], v[20:21], v[24:25] op_sel_hi:[0,1]
	v_pk_mul_f32 v[10:11], v[10:11], v[14:15]
	v_pk_mul_f32 v[14:15], v[16:17], v[18:19] op_sel_hi:[1,0]
	s_nop 0
	v_exp_f32_e32 v14, v14
	v_exp_f32_e32 v15, v15
	s_nop 0
	v_pk_add_f32 v[14:15], v[14:15], 1.0 op_sel_hi:[1,0]
	s_nop 0
	v_rcp_f32_e32 v14, v14
	v_rcp_f32_e32 v15, v15
	s_nop 0
	v_pk_mul_f32 v[14:15], v[20:21], v[14:15] op_sel_hi:[0,1]
	v_pk_mul_f32 v[12:13], v[12:13], v[14:15]
	v_pk_mul_f32 v[14:15], v[6:7], v[18:19] op_sel_hi:[1,0]
	s_nop 0
	v_exp_f32_e32 v14, v14
	v_exp_f32_e32 v15, v15
	s_nop 0
	v_pk_add_f32 v[14:15], v[14:15], 1.0 op_sel_hi:[1,0]
	s_nop 0
	v_rcp_f32_e32 v14, v14
	v_rcp_f32_e32 v15, v15
	s_nop 0
	v_pk_mul_f32 v[6:7], v[20:21], v[14:15] op_sel_hi:[0,1]
	v_pk_mul_f32 v[6:7], v[2:3], v[6:7]
	v_pk_mul_f32 v[2:3], v[8:9], v[18:19] op_sel_hi:[1,0]
	s_nop 0
	v_exp_f32_e32 v2, v2
	v_exp_f32_e32 v3, v3
	s_nop 0
	v_pk_add_f32 v[2:3], v[2:3], 1.0 op_sel_hi:[1,0]
	s_nop 0
	v_rcp_f32_e32 v2, v2
	v_rcp_f32_e32 v3, v3
	s_nop 0
	v_pk_mul_f32 v[2:3], v[20:21], v[2:3] op_sel_hi:[0,1]
	v_pk_mul_f32 v[8:9], v[4:5], v[2:3]
	v_cvt_pk_bf16_f32 v2, v10, v11
	v_cvt_pk_bf16_f32 v3, v12, v13
	v_cvt_pk_bf16_f32 v4, v6, v7
	s_nop 0
	v_cvt_pk_bf16_f32 v5, v8, v9
	flat_store_dwordx4 v[22:23], v[2:5]
	s_cbranch_vccnz .LBB0_170
	s_andn2_b64 vcc, exec, s[10:11]
	s_cbranch_vccnz .LBB0_169
	s_barrier
	s_branch .LBB0_169
